# gate-up tile loop: early wave half runs its SwiGLU epilogue before (not after) the re-alignment barrier, overlapping the other half's last MFMA segment
# baseline (speedup 1.0000x reference)
; #define PG8_STAGE(bufoff, gbase, voff) do { _Pragma("unroll") for (int _i = 0; _i < 2; ++_i) { \
;         const unsigned _m0 = ldsb + (unsigned)((bufoff) + _i * 8192); const char* _gb = (const char*)(gbase); \
;         asm volatile("s_mov_b32 m0, %0\n\ts_nop 0\n\tglobal_load_lds_dwordx4 %1, %2" :: "s"(_m0), "v"((voff)[_i]), "s"(_gb) : "m0", "memory"); } } while (0)
; #define PG8_LDA(dst, b, h) do { _Pragma("unroll") for (int m = 0; m < 4; ++m) _Pragma("unroll") for (int k = 0; k < 2; ++k) dst[m][k] = *(const LAS bf16x8*)(lds + PG8_SA(b, h) + aoff + m * 2048 + k * 1024); } while (0)
; #define PG8_LDB(dst, b, h) do { _Pragma("unroll") for (int n = 0; n < 2; ++n) _Pragma("unroll") for (int k = 0; k < 2; ++k) dst[n][k] = *(const LAS bf16x8*)(lds + PG8_SB(b, h) + boff + n * 2048 + k * 1024); } while (0)
; #define PG8_MMA(ai, bj, At, Bt) do { __builtin_amdgcn_s_setprio(1); _Pragma("unroll") for (int m = 0; m < 4; ++m) _Pragma("unroll") for (int n = 0; n < 2; ++n) _Pragma("unroll") for (int k = 0; k < 2; ++k) \
;         acc[ai][bj][m][n] = __builtin_amdgcn_mfma_f32_16x16x32_bf16(Bt[n][k], At[m][k], acc[ai][bj][m][n], 0, 0, 0); __builtin_amdgcn_s_setprio(0); } while (0)
; #define PG8_WAIT_V(n) asm volatile("s_waitcnt vmcnt(" #n ")" ::: "memory")
; #define PG8_WAIT_L(n) asm volatile("s_waitcnt lgkmcnt(" #n ")" ::: "memory")
; #define PG8_BAR __builtin_amdgcn_s_barrier()
; #define PG8_SCHED __builtin_amdgcn_sched_barrier(0)
; template <class Epi, bool ALIGN_EPI>
; __device__ __forceinline__ void gemm_phase(LAS unsigned char* lds, const Gemm g, const StaticOrder& S, const Epi& E) {
;     ...
;             PG8_LDB(B0, 0, 0); PG8_LDB(B1, 0, 1); PG8_SCHED; PG8_LDA(At, 0, 0); PG8_STAGE(PG8_SA(1, 1), a1 + hstepA, voffA);
;             PG8_WAIT_V(8); PG8_WAIT_L(0); PG8_BAR; PG8_MMA(0, 0, At, B0); PG8_MMA(0, 1, At, B1); PG8_BAR; PG8_SCHED;
;             PG8_LDA(At, 0, 1); PG8_STAGE(PG8_SB(0, 0), b2, voffB); PG8_STAGE(PG8_SB(0, 1), b2 + hstepB, voffB); PG8_STAGE(PG8_SA(0, 0), a2, voffA);
;             PG8_WAIT_V(8); PG8_WAIT_L(0); PG8_BAR; PG8_MMA(1, 0, At, B0); PG8_MMA(1, 1, At, B1); PG8_BAR; PG8_SCHED;
;             PG8_LDB(B0, 1, 0); PG8_LDB(B1, 1, 1); PG8_SCHED; PG8_LDA(At, 1, 0); PG8_STAGE(PG8_SA(0, 1), a2 + hstepA, voffA);
;             PG8_WAIT_V(8); PG8_WAIT_L(0); PG8_BAR; PG8_MMA(0, 0, At, B0); PG8_MMA(0, 1, At, B1); PG8_BAR; PG8_SCHED;
.LBB0_306:
	v_add_u32_e32 v134, 0x10000, v185
	v_add_u32_e32 v158, 0x14000, v185
	ds_read_b128 v[74:77], v134
	ds_read_b128 v[94:97], v134 offset:1024
	ds_read_b128 v[114:117], v134 offset:2048
	ds_read_b128 v[134:137], v134 offset:3072
	ds_read_b128 v[146:149], v158
	ds_read_b128 v[150:153], v158 offset:1024
	ds_read_b128 v[154:157], v158 offset:2048
	ds_read_b128 v[158:161], v158 offset:3072
	s_add_u32 s30, s92, 0xfffc0080
	s_addc_u32 s31, s93, -1
	s_cmp_eq_u32 s50, 12
	s_cselect_b32 s60, s5, s30
	s_cselect_b32 s61, s4, s31
	s_cselect_b32 s58, s37, s41
	s_cselect_b32 s59, s35, s49
	s_add_u32 s56, s60, 0x80
	s_addc_u32 s57, s61, 0
	ds_read_b128 v[162:165], v186
	ds_read_b128 v[166:169], v186 offset:1024
	ds_read_b128 v[170:173], v186 offset:2048
	ds_read_b128 v[174:177], v186 offset:3072
	ds_read_b128 v[188:191], v186 offset:4096
	ds_read_b128 v[202:205], v186 offset:5120
	ds_read_b128 v[206:209], v186 offset:6144
	ds_read_b128 v[210:213], v186 offset:7168
	s_mov_b32 m0, s67
	s_nop 0
	global_load_lds_dwordx4 v0, s[92:93]
	s_nop 0
	s_mov_b32 m0, s65
	s_nop 0
	global_load_lds_dwordx4 v181, s[92:93]
	s_waitcnt vmcnt(8)
	s_waitcnt lgkmcnt(0)
	s_setprio 1
	s_barrier
	v_mfma_f32_16x16x32_bf16 v[142:145], v[74:77], v[162:165], v[142:145]
	v_mfma_f32_16x16x32_bf16 v[142:145], v[94:97], v[166:169], v[142:145]
	v_mfma_f32_16x16x32_bf16 v[138:141], v[114:117], v[162:165], v[138:141]
	v_mfma_f32_16x16x32_bf16 v[138:141], v[134:137], v[166:169], v[138:141]
	v_mfma_f32_16x16x32_bf16 v[130:133], v[146:149], v[162:165], v[130:133]
	v_mfma_f32_16x16x32_bf16 v[130:133], v[150:153], v[166:169], v[130:133]
	v_mfma_f32_16x16x32_bf16 v[126:129], v[154:157], v[162:165], v[126:129]
	v_mfma_f32_16x16x32_bf16 v[126:129], v[158:161], v[166:169], v[126:129]
	v_mfma_f32_16x16x32_bf16 v[106:109], v[154:157], v[170:173], v[106:109]
	v_mfma_f32_16x16x32_bf16 v[106:109], v[158:161], v[174:177], v[106:109]
	v_mfma_f32_16x16x32_bf16 v[110:113], v[146:149], v[170:173], v[110:113]
	v_mfma_f32_16x16x32_bf16 v[110:113], v[150:153], v[174:177], v[110:113]
	v_mfma_f32_16x16x32_bf16 v[118:121], v[114:117], v[170:173], v[118:121]
	v_mfma_f32_16x16x32_bf16 v[118:121], v[134:137], v[174:177], v[118:121]
	v_mfma_f32_16x16x32_bf16 v[122:125], v[74:77], v[170:173], v[122:125]
	v_mfma_f32_16x16x32_bf16 v[122:125], v[94:97], v[174:177], v[122:125]
	v_mfma_f32_16x16x32_bf16 v[102:105], v[74:77], v[188:191], v[102:105]
	v_mfma_f32_16x16x32_bf16 v[102:105], v[94:97], v[202:205], v[102:105]
	v_mfma_f32_16x16x32_bf16 v[98:101], v[114:117], v[188:191], v[98:101]
	v_mfma_f32_16x16x32_bf16 v[98:101], v[134:137], v[202:205], v[98:101]
	v_mfma_f32_16x16x32_bf16 v[90:93], v[146:149], v[188:191], v[90:93]
	v_mfma_f32_16x16x32_bf16 v[90:93], v[150:153], v[202:205], v[90:93]
	v_mfma_f32_16x16x32_bf16 v[86:89], v[154:157], v[188:191], v[86:89]
	v_mfma_f32_16x16x32_bf16 v[86:89], v[158:161], v[202:205], v[86:89]
	v_mfma_f32_16x16x32_bf16 v[66:69], v[154:157], v[206:209], v[66:69]
	v_mfma_f32_16x16x32_bf16 v[66:69], v[158:161], v[210:213], v[66:69]
	v_mfma_f32_16x16x32_bf16 v[70:73], v[146:149], v[206:209], v[70:73]
	v_mfma_f32_16x16x32_bf16 v[70:73], v[150:153], v[210:213], v[70:73]
	v_mfma_f32_16x16x32_bf16 v[78:81], v[114:117], v[206:209], v[78:81]
	v_mfma_f32_16x16x32_bf16 v[78:81], v[134:137], v[210:213], v[78:81]
	v_mfma_f32_16x16x32_bf16 v[82:85], v[74:77], v[206:209], v[82:85]
	v_mfma_f32_16x16x32_bf16 v[82:85], v[94:97], v[210:213], v[82:85]
	s_barrier
	s_setprio 0
	ds_read_b128 v[162:165], v186 offset:16384
	ds_read_b128 v[166:169], v186 offset:17408
	ds_read_b128 v[170:173], v186 offset:18432
	ds_read_b128 v[174:177], v186 offset:19456
	ds_read_b128 v[188:191], v186 offset:20480
	ds_read_b128 v[202:205], v186 offset:21504
	ds_read_b128 v[206:209], v186 offset:22528
	ds_read_b128 v[210:213], v186 offset:23552
	s_mov_b32 m0, s29
	s_nop 0
	global_load_lds_dwordx4 v180, s[58:59]
	s_add_u32 s30, s58, 0x40000
	s_mov_b32 m0, s42
	s_nop 0
	global_load_lds_dwordx4 v182, s[58:59]
	s_addc_u32 s31, s59, 0
	s_mov_b32 m0, s43
	s_nop 0
	global_load_lds_dwordx4 v180, s[30:31]
	s_nop 0
	s_mov_b32 m0, s44
	s_nop 0
	global_load_lds_dwordx4 v182, s[30:31]
	s_nop 0
	s_mov_b32 m0, s15
	s_nop 0
	global_load_lds_dwordx4 v0, s[60:61]
	s_nop 0
	s_mov_b32 m0, s45
	s_nop 0
	global_load_lds_dwordx4 v181, s[60:61]
	s_waitcnt vmcnt(8)
	s_waitcnt lgkmcnt(0)
	s_setprio 1
	s_barrier
	v_mfma_f32_16x16x32_bf16 v[62:65], v[74:77], v[162:165], v[62:65]
	v_mfma_f32_16x16x32_bf16 v[62:65], v[94:97], v[166:169], v[62:65]
	v_mfma_f32_16x16x32_bf16 v[58:61], v[114:117], v[162:165], v[58:61]
	v_mfma_f32_16x16x32_bf16 v[58:61], v[134:137], v[166:169], v[58:61]
	v_mfma_f32_16x16x32_bf16 v[54:57], v[146:149], v[162:165], v[54:57]
	v_mfma_f32_16x16x32_bf16 v[54:57], v[150:153], v[166:169], v[54:57]
	v_mfma_f32_16x16x32_bf16 v[50:53], v[154:157], v[162:165], v[50:53]
	v_mfma_f32_16x16x32_bf16 v[50:53], v[158:161], v[166:169], v[50:53]
	v_mfma_f32_16x16x32_bf16 v[34:37], v[154:157], v[170:173], v[34:37]
	v_mfma_f32_16x16x32_bf16 v[34:37], v[158:161], v[174:177], v[34:37]
	v_mfma_f32_16x16x32_bf16 v[38:41], v[146:149], v[170:173], v[38:41]
	v_mfma_f32_16x16x32_bf16 v[38:41], v[150:153], v[174:177], v[38:41]
	v_mfma_f32_16x16x32_bf16 v[42:45], v[114:117], v[170:173], v[42:45]
	v_mfma_f32_16x16x32_bf16 v[42:45], v[134:137], v[174:177], v[42:45]
	v_mfma_f32_16x16x32_bf16 v[46:49], v[74:77], v[170:173], v[46:49]
	v_mfma_f32_16x16x32_bf16 v[46:49], v[94:97], v[174:177], v[46:49]
	v_mfma_f32_16x16x32_bf16 v[30:33], v[74:77], v[188:191], v[30:33]
	v_mfma_f32_16x16x32_bf16 v[30:33], v[94:97], v[202:205], v[30:33]
	v_mfma_f32_16x16x32_bf16 v[26:29], v[114:117], v[188:191], v[26:29]
	v_mfma_f32_16x16x32_bf16 v[26:29], v[134:137], v[202:205], v[26:29]
	v_mfma_f32_16x16x32_bf16 v[22:25], v[146:149], v[188:191], v[22:25]
	v_mfma_f32_16x16x32_bf16 v[22:25], v[150:153], v[202:205], v[22:25]
	v_mfma_f32_16x16x32_bf16 v[18:21], v[154:157], v[188:191], v[18:21]
	v_mfma_f32_16x16x32_bf16 v[18:21], v[158:161], v[202:205], v[18:21]
	v_mfma_f32_16x16x32_bf16 v[2:5], v[154:157], v[206:209], v[2:5]
	v_mfma_f32_16x16x32_bf16 v[2:5], v[158:161], v[210:213], v[2:5]
	v_mfma_f32_16x16x32_bf16 v[6:9], v[146:149], v[206:209], v[6:9]
	v_mfma_f32_16x16x32_bf16 v[6:9], v[150:153], v[210:213], v[6:9]
	v_mfma_f32_16x16x32_bf16 v[10:13], v[114:117], v[206:209], v[10:13]
	v_mfma_f32_16x16x32_bf16 v[10:13], v[134:137], v[210:213], v[10:13]
	v_mfma_f32_16x16x32_bf16 v[14:17], v[74:77], v[206:209], v[14:17]
	v_mfma_f32_16x16x32_bf16 v[14:17], v[94:97], v[210:213], v[14:17]
	s_barrier
; #define PG8_STAGE(bufoff, gbase, voff) do { _Pragma("unroll") for (int _i = 0; _i < 2; ++_i) { \
;         const unsigned _m0 = ldsb + (unsigned)((bufoff) + _i * 8192); const char* _gb = (const char*)(gbase); \
;         asm volatile("s_mov_b32 m0, %0\n\ts_nop 0\n\tglobal_load_lds_dwordx4 %1, %2" :: "s"(_m0), "v"((voff)[_i]), "s"(_gb) : "m0", "memory"); } } while (0)
; #define PG8_LDA(dst, b, h) do { _Pragma("unroll") for (int m = 0; m < 4; ++m) _Pragma("unroll") for (int k = 0; k < 2; ++k) dst[m][k] = *(const LAS bf16x8*)(lds + PG8_SA(b, h) + aoff + m * 2048 + k * 1024); } while (0)
; #define PG8_MMA(ai, bj, At, Bt) do { __builtin_amdgcn_s_setprio(1); _Pragma("unroll") for (int m = 0; m < 4; ++m) _Pragma("unroll") for (int n = 0; n < 2; ++n) _Pragma("unroll") for (int k = 0; k < 2; ++k) \
;         acc[ai][bj][m][n] = __builtin_amdgcn_mfma_f32_16x16x32_bf16(Bt[n][k], At[m][k], acc[ai][bj][m][n], 0, 0, 0); __builtin_amdgcn_s_setprio(0); } while (0)
; #define PG8_WAIT_V(n) asm volatile("s_waitcnt vmcnt(" #n ")" ::: "memory")
; #define PG8_WAIT_L(n) asm volatile("s_waitcnt lgkmcnt(" #n ")" ::: "memory")
; #define PG8_BAR __builtin_amdgcn_s_barrier()
; #define PG8_SCHED __builtin_amdgcn_sched_barrier(0)
; template <class Epi, bool ALIGN_EPI>
; __device__ __forceinline__ void gemm_phase(LAS unsigned char* lds, const Gemm g, const StaticOrder& S, const Epi& E) {
;     ...
;             PG8_LDA(At, 1, 1); PG8_STAGE(PG8_SB(1, 0), b3, voffB); PG8_STAGE(PG8_SB(1, 1), b3 + hstepB, voffB); PG8_STAGE(PG8_SA(1, 0), a3, voffA);
;             PG8_WAIT_V(8); PG8_WAIT_L(0); PG8_BAR; PG8_MMA(1, 0, At, B0); PG8_MMA(1, 1, At, B1); PG8_BAR; PG8_SCHED;
;         }
;         if constexpr (ALIGN_EPI) { if (wr == 0) PG8_BAR; }
	s_setprio 0
	v_add_u32_e32 v134, 0x18000, v185
	v_add_u32_e32 v158, 0x1c000, v185
	ds_read_b128 v[74:77], v134
	ds_read_b128 v[94:97], v134 offset:1024
	ds_read_b128 v[114:117], v134 offset:2048
	ds_read_b128 v[134:137], v134 offset:3072
	ds_read_b128 v[146:149], v158
	ds_read_b128 v[150:153], v158 offset:1024
	ds_read_b128 v[154:157], v158 offset:2048
	ds_read_b128 v[158:161], v158 offset:3072
	ds_read_b128 v[162:165], v186 offset:32768
	ds_read_b128 v[166:169], v186 offset:33792
	ds_read_b128 v[170:173], v186 offset:34816
	ds_read_b128 v[174:177], v186 offset:35840
	ds_read_b128 v[188:191], v186 offset:36864
	ds_read_b128 v[202:205], v186 offset:37888
	ds_read_b128 v[206:209], v186 offset:38912
	ds_read_b128 v[210:213], v186 offset:39936
	s_add_u32 s30, s60, 0x40000
	s_addc_u32 s31, s61, 0
	s_mov_b32 m0, s55
	s_nop 0
	global_load_lds_dwordx4 v0, s[30:31]
	s_nop 0
	s_mov_b32 m0, s88
	s_nop 0
	global_load_lds_dwordx4 v181, s[30:31]
	s_waitcnt vmcnt(8)
	s_waitcnt lgkmcnt(0)
	s_setprio 1
	s_barrier
	v_mfma_f32_16x16x32_bf16 v[142:145], v[74:77], v[162:165], v[142:145]
	v_mfma_f32_16x16x32_bf16 v[142:145], v[94:97], v[166:169], v[142:145]
	v_mfma_f32_16x16x32_bf16 v[138:141], v[114:117], v[162:165], v[138:141]
	v_mfma_f32_16x16x32_bf16 v[138:141], v[134:137], v[166:169], v[138:141]
	v_mfma_f32_16x16x32_bf16 v[130:133], v[146:149], v[162:165], v[130:133]
	v_mfma_f32_16x16x32_bf16 v[130:133], v[150:153], v[166:169], v[130:133]
	v_mfma_f32_16x16x32_bf16 v[126:129], v[154:157], v[162:165], v[126:129]
	v_mfma_f32_16x16x32_bf16 v[126:129], v[158:161], v[166:169], v[126:129]
	v_mfma_f32_16x16x32_bf16 v[106:109], v[154:157], v[170:173], v[106:109]
	v_mfma_f32_16x16x32_bf16 v[106:109], v[158:161], v[174:177], v[106:109]
	v_mfma_f32_16x16x32_bf16 v[110:113], v[146:149], v[170:173], v[110:113]
	v_mfma_f32_16x16x32_bf16 v[110:113], v[150:153], v[174:177], v[110:113]
	v_mfma_f32_16x16x32_bf16 v[118:121], v[114:117], v[170:173], v[118:121]
	v_mfma_f32_16x16x32_bf16 v[118:121], v[134:137], v[174:177], v[118:121]
	v_mfma_f32_16x16x32_bf16 v[122:125], v[74:77], v[170:173], v[122:125]
	v_mfma_f32_16x16x32_bf16 v[122:125], v[94:97], v[174:177], v[122:125]
	v_mfma_f32_16x16x32_bf16 v[102:105], v[74:77], v[188:191], v[102:105]
	v_mfma_f32_16x16x32_bf16 v[102:105], v[94:97], v[202:205], v[102:105]
	v_mfma_f32_16x16x32_bf16 v[98:101], v[114:117], v[188:191], v[98:101]
	v_mfma_f32_16x16x32_bf16 v[98:101], v[134:137], v[202:205], v[98:101]
	v_mfma_f32_16x16x32_bf16 v[90:93], v[146:149], v[188:191], v[90:93]
	v_mfma_f32_16x16x32_bf16 v[90:93], v[150:153], v[202:205], v[90:93]
	v_mfma_f32_16x16x32_bf16 v[86:89], v[154:157], v[188:191], v[86:89]
	v_mfma_f32_16x16x32_bf16 v[86:89], v[158:161], v[202:205], v[86:89]
	v_mfma_f32_16x16x32_bf16 v[66:69], v[154:157], v[206:209], v[66:69]
	v_mfma_f32_16x16x32_bf16 v[66:69], v[158:161], v[210:213], v[66:69]
	v_mfma_f32_16x16x32_bf16 v[70:73], v[146:149], v[206:209], v[70:73]
	v_mfma_f32_16x16x32_bf16 v[70:73], v[150:153], v[210:213], v[70:73]
	v_mfma_f32_16x16x32_bf16 v[78:81], v[114:117], v[206:209], v[78:81]
	v_mfma_f32_16x16x32_bf16 v[78:81], v[134:137], v[210:213], v[78:81]
	v_mfma_f32_16x16x32_bf16 v[82:85], v[74:77], v[206:209], v[82:85]
	v_mfma_f32_16x16x32_bf16 v[82:85], v[94:97], v[210:213], v[82:85]
	s_barrier
	s_setprio 0
	ds_read_b128 v[162:165], v186 offset:49152
	ds_read_b128 v[166:169], v186 offset:50176
	ds_read_b128 v[170:173], v186 offset:51200
	ds_read_b128 v[174:177], v186 offset:52224
	ds_read_b128 v[188:191], v186 offset:53248
	ds_read_b128 v[202:205], v186 offset:54272
	ds_read_b128 v[206:209], v186 offset:55296
	ds_read_b128 v[210:213], v186 offset:56320
	s_add_u32 s30, s58, 0x80
	s_addc_u32 s31, s59, 0
	s_mov_b32 m0, s94
	s_nop 0
	global_load_lds_dwordx4 v180, s[30:31]
	s_nop 0
	s_mov_b32 m0, s95
	s_nop 0
	global_load_lds_dwordx4 v182, s[30:31]
	s_add_u32 s30, s58, 0x40080
	s_addc_u32 s31, s59, 0
	s_mov_b32 m0, s17
	s_nop 0
	global_load_lds_dwordx4 v180, s[30:31]
	s_nop 0
	s_mov_b32 m0, s53
	s_nop 0
	global_load_lds_dwordx4 v182, s[30:31]
	s_nop 0
	s_mov_b32 m0, s96
	s_nop 0
	global_load_lds_dwordx4 v0, s[56:57]
	s_nop 0
	s_mov_b32 m0, s97
	s_nop 0
	global_load_lds_dwordx4 v181, s[56:57]
	s_waitcnt vmcnt(8)
	s_waitcnt lgkmcnt(0)
	s_setprio 1
	s_barrier
	v_mfma_f32_16x16x32_bf16 v[62:65], v[74:77], v[162:165], v[62:65]
	v_mfma_f32_16x16x32_bf16 v[62:65], v[94:97], v[166:169], v[62:65]
	v_mfma_f32_16x16x32_bf16 v[58:61], v[114:117], v[162:165], v[58:61]
	v_mfma_f32_16x16x32_bf16 v[58:61], v[134:137], v[166:169], v[58:61]
	v_mfma_f32_16x16x32_bf16 v[54:57], v[146:149], v[162:165], v[54:57]
	v_mfma_f32_16x16x32_bf16 v[54:57], v[150:153], v[166:169], v[54:57]
	v_mfma_f32_16x16x32_bf16 v[50:53], v[154:157], v[162:165], v[50:53]
	v_mfma_f32_16x16x32_bf16 v[50:53], v[158:161], v[166:169], v[50:53]
	v_mfma_f32_16x16x32_bf16 v[34:37], v[154:157], v[170:173], v[34:37]
	v_mfma_f32_16x16x32_bf16 v[34:37], v[158:161], v[174:177], v[34:37]
	v_mfma_f32_16x16x32_bf16 v[38:41], v[146:149], v[170:173], v[38:41]
	v_mfma_f32_16x16x32_bf16 v[38:41], v[150:153], v[174:177], v[38:41]
	v_mfma_f32_16x16x32_bf16 v[42:45], v[114:117], v[170:173], v[42:45]
	v_mfma_f32_16x16x32_bf16 v[42:45], v[134:137], v[174:177], v[42:45]
	v_mfma_f32_16x16x32_bf16 v[46:49], v[74:77], v[170:173], v[46:49]
	v_mfma_f32_16x16x32_bf16 v[46:49], v[94:97], v[174:177], v[46:49]
	v_mfma_f32_16x16x32_bf16 v[30:33], v[74:77], v[188:191], v[30:33]
	v_mfma_f32_16x16x32_bf16 v[30:33], v[94:97], v[202:205], v[30:33]
	v_mfma_f32_16x16x32_bf16 v[26:29], v[114:117], v[188:191], v[26:29]
	v_mfma_f32_16x16x32_bf16 v[26:29], v[134:137], v[202:205], v[26:29]
	v_mfma_f32_16x16x32_bf16 v[22:25], v[146:149], v[188:191], v[22:25]
	v_mfma_f32_16x16x32_bf16 v[22:25], v[150:153], v[202:205], v[22:25]
	v_mfma_f32_16x16x32_bf16 v[18:21], v[154:157], v[188:191], v[18:21]
	v_mfma_f32_16x16x32_bf16 v[18:21], v[158:161], v[202:205], v[18:21]
	v_mfma_f32_16x16x32_bf16 v[2:5], v[154:157], v[206:209], v[2:5]
	v_mfma_f32_16x16x32_bf16 v[2:5], v[158:161], v[210:213], v[2:5]
	v_mfma_f32_16x16x32_bf16 v[6:9], v[146:149], v[206:209], v[6:9]
	v_mfma_f32_16x16x32_bf16 v[6:9], v[150:153], v[210:213], v[6:9]
	v_mfma_f32_16x16x32_bf16 v[10:13], v[114:117], v[206:209], v[10:13]
	v_mfma_f32_16x16x32_bf16 v[10:13], v[134:137], v[210:213], v[10:13]
	v_mfma_f32_16x16x32_bf16 v[14:17], v[74:77], v[206:209], v[14:17]
	v_mfma_f32_16x16x32_bf16 v[14:17], v[94:97], v[210:213], v[14:17]
	s_barrier
	s_setprio 0
	s_add_i32 s50, s50, 2
	s_add_u32 s41, s41, 0x100
	s_addc_u32 s49, s49, 0
	s_add_u32 s92, s92, 0x100
	s_addc_u32 s93, s93, 0
	s_cmp_gt_u32 s50, 13
	s_cbranch_scc0 .LBB0_306
	s_and_b64 vcc, exec, s[6:7]
	s_cbranch_vccz .Lep_fast
	v_readlane_b32 s4, v254, 46
	v_readlane_b32 s5, v254, 47
	s_and_b64 vcc, exec, s[4:5]
	s_cbranch_vccz .LBB0_309
	s_barrier

; __device__ __forceinline__ unsigned cvt_pk_bf16(float lo, float hi) { unsigned r; asm volatile("v_cvt_pk_bf16_f32 %0, %1, %2" : "=v"(r) : "v"(lo), "v"(hi)); return r; }
; __device__ __forceinline__ float silu_f(float g) { return g * __builtin_amdgcn_rcpf(1.0f + __builtin_amdgcn_exp2f(g * -1.4426950408889634f)); }
;     __device__ __forceinline__ void operator()(const f32x4 (&acc)[2][2][4][2], const Unit& u, int wr, int wc, int fr, int fq) const {
;     ...
;             for (int m = 0; m < 4; ++m) { const int row = row0 + ai * HALF + m * 16; const float rs = rsv[ai][m];
;                 f32x4 g0 = acc[ai][0][m][0] * rs, g1 = acc[ai][0][m][1] * rs; const f32x4 t0 = acc[ai][1][m][0] * rs, t1 = acc[ai][1][m][1] * rs;
;                 if (silu) {
; #pragma unroll
;                     for (int j = 0; j < 4; ++j) { g0[j] = silu_f(g0[j]); g1[j] = silu_f(g1[j]); } }
;                 g0 = g0 * t0; g1 = g1 * t1;
;                 u32x4 w; w.x = cvt_pk_bf16(g0[0], g0[1]); w.y = cvt_pk_bf16(g0[2], g0[3]); w.z = cvt_pk_bf16(g1[0], g1[1]); w.w = cvt_pk_bf16(g1[2], g1[3]);
;                 *(u32x4*)(O + (size_t)row * ldc + col0 + (size_t)(row >> 12) * adj) = w; }
.Lep_have_rs:
	v_pk_mul_f32 v[146:147], v[142:143], v[240:241] op_sel_hi:[1,0]
	v_pk_mul_f32 v[148:149], v[144:145], v[240:241] op_sel_hi:[1,0]
	v_pk_mul_f32 v[150:151], v[138:139], v[240:241] op_sel_hi:[1,0]
	v_pk_mul_f32 v[152:153], v[140:141], v[240:241] op_sel_hi:[1,0]
	v_exp_f32_e32 v146, v146
	v_exp_f32_e32 v147, v147
	v_exp_f32_e32 v148, v148
	v_exp_f32_e32 v149, v149
	v_exp_f32_e32 v150, v150
	v_exp_f32_e32 v151, v151
	v_exp_f32_e32 v152, v152
	v_exp_f32_e32 v153, v153
	v_pk_mul_f32 v[142:143], v[142:143], v[130:131]
	v_pk_mul_f32 v[144:145], v[144:145], v[132:133]
	v_pk_mul_f32 v[138:139], v[138:139], v[126:127]
	v_pk_mul_f32 v[140:141], v[140:141], v[128:129]
	v_pk_fma_f32 v[146:147], v[146:147], v[240:241], v[240:241] op_sel:[0,1,1] op_sel_hi:[1,1,1]
	v_pk_fma_f32 v[148:149], v[148:149], v[240:241], v[240:241] op_sel:[0,1,1] op_sel_hi:[1,1,1]
	v_pk_fma_f32 v[150:151], v[150:151], v[240:241], v[240:241] op_sel:[0,1,1] op_sel_hi:[1,1,1]
	v_pk_fma_f32 v[152:153], v[152:153], v[240:241], v[240:241] op_sel:[0,1,1] op_sel_hi:[1,1,1]
	v_rcp_f32_e32 v146, v146
	v_rcp_f32_e32 v147, v147
	v_rcp_f32_e32 v148, v148
	v_rcp_f32_e32 v149, v149
	v_rcp_f32_e32 v150, v150
	v_rcp_f32_e32 v151, v151
	v_rcp_f32_e32 v152, v152
	v_rcp_f32_e32 v153, v153
	v_pk_mul_f32 v[154:155], v[122:123], v[242:243] op_sel_hi:[1,0]
	v_pk_mul_f32 v[156:157], v[124:125], v[242:243] op_sel_hi:[1,0]
	v_pk_mul_f32 v[158:159], v[118:119], v[242:243] op_sel_hi:[1,0]
	v_pk_mul_f32 v[160:161], v[120:121], v[242:243] op_sel_hi:[1,0]
	v_pk_mul_f32 v[142:143], v[142:143], v[146:147]
	v_pk_mul_f32 v[144:145], v[144:145], v[148:149]
	v_pk_mul_f32 v[138:139], v[138:139], v[150:151]
	v_pk_mul_f32 v[140:141], v[140:141], v[152:153]
	v_cvt_pk_bf16_f32 v162, v142, v143
	v_cvt_pk_bf16_f32 v163, v144, v145
	v_cvt_pk_bf16_f32 v164, v138, v139
	v_cvt_pk_bf16_f32 v165, v140, v141
	global_store_dwordx4 v190, v[162:165], s[10:11] sc1
	v_add_u32_e32 v190, s30, v190
	v_exp_f32_e32 v154, v154
	v_exp_f32_e32 v155, v155
	v_exp_f32_e32 v156, v156
	v_exp_f32_e32 v157, v157
	v_exp_f32_e32 v158, v158
	v_exp_f32_e32 v159, v159
	v_exp_f32_e32 v160, v160
	v_exp_f32_e32 v161, v161
	v_pk_mul_f32 v[122:123], v[122:123], v[110:111]
	v_pk_mul_f32 v[124:125], v[124:125], v[112:113]
	v_pk_mul_f32 v[118:119], v[118:119], v[106:107]
	v_pk_mul_f32 v[120:121], v[120:121], v[108:109]
	v_pk_fma_f32 v[154:155], v[154:155], v[242:243], v[242:243] op_sel:[0,1,1] op_sel_hi:[1,1,1]
	v_pk_fma_f32 v[156:157], v[156:157], v[242:243], v[242:243] op_sel:[0,1,1] op_sel_hi:[1,1,1]
	v_pk_fma_f32 v[158:159], v[158:159], v[242:243], v[242:243] op_sel:[0,1,1] op_sel_hi:[1,1,1]
	v_pk_fma_f32 v[160:161], v[160:161], v[242:243], v[242:243] op_sel:[0,1,1] op_sel_hi:[1,1,1]
	v_rcp_f32_e32 v154, v154
	v_rcp_f32_e32 v155, v155
	v_rcp_f32_e32 v156, v156
	v_rcp_f32_e32 v157, v157
	v_rcp_f32_e32 v158, v158
	v_rcp_f32_e32 v159, v159
	v_rcp_f32_e32 v160, v160
	v_rcp_f32_e32 v161, v161
	v_pk_mul_f32 v[146:147], v[102:103], v[244:245] op_sel_hi:[1,0]
	v_pk_mul_f32 v[148:149], v[104:105], v[244:245] op_sel_hi:[1,0]
	v_pk_mul_f32 v[150:151], v[98:99], v[244:245] op_sel_hi:[1,0]
	v_pk_mul_f32 v[152:153], v[100:101], v[244:245] op_sel_hi:[1,0]
	v_pk_mul_f32 v[122:123], v[122:123], v[154:155]
	v_pk_mul_f32 v[124:125], v[124:125], v[156:157]
	v_pk_mul_f32 v[118:119], v[118:119], v[158:159]
	v_pk_mul_f32 v[120:121], v[120:121], v[160:161]
	v_cvt_pk_bf16_f32 v166, v122, v123
	v_cvt_pk_bf16_f32 v167, v124, v125
	v_cvt_pk_bf16_f32 v168, v118, v119
	v_cvt_pk_bf16_f32 v169, v120, v121
	global_store_dwordx4 v190, v[166:169], s[10:11] sc1
	v_add_u32_e32 v190, s30, v190
	v_exp_f32_e32 v146, v146
	v_exp_f32_e32 v147, v147
	v_exp_f32_e32 v148, v148
	v_exp_f32_e32 v149, v149
	v_exp_f32_e32 v150, v150
	v_exp_f32_e32 v151, v151
	v_exp_f32_e32 v152, v152
	v_exp_f32_e32 v153, v153
	v_pk_mul_f32 v[102:103], v[102:103], v[90:91]
	v_pk_mul_f32 v[104:105], v[104:105], v[92:93]
	v_pk_mul_f32 v[98:99], v[98:99], v[86:87]
	v_pk_mul_f32 v[100:101], v[100:101], v[88:89]
	v_pk_fma_f32 v[146:147], v[146:147], v[244:245], v[244:245] op_sel:[0,1,1] op_sel_hi:[1,1,1]
	v_pk_fma_f32 v[148:149], v[148:149], v[244:245], v[244:245] op_sel:[0,1,1] op_sel_hi:[1,1,1]
	v_pk_fma_f32 v[150:151], v[150:151], v[244:245], v[244:245] op_sel:[0,1,1] op_sel_hi:[1,1,1]
	v_pk_fma_f32 v[152:153], v[152:153], v[244:245], v[244:245] op_sel:[0,1,1] op_sel_hi:[1,1,1]
	v_rcp_f32_e32 v146, v146
	v_rcp_f32_e32 v147, v147
	v_rcp_f32_e32 v148, v148
	v_rcp_f32_e32 v149, v149
	v_rcp_f32_e32 v150, v150
	v_rcp_f32_e32 v151, v151
	v_rcp_f32_e32 v152, v152
	v_rcp_f32_e32 v153, v153
	v_pk_mul_f32 v[154:155], v[82:83], v[246:247] op_sel_hi:[1,0]
	v_pk_mul_f32 v[156:157], v[84:85], v[246:247] op_sel_hi:[1,0]
	v_pk_mul_f32 v[158:159], v[78:79], v[246:247] op_sel_hi:[1,0]
	v_pk_mul_f32 v[160:161], v[80:81], v[246:247] op_sel_hi:[1,0]
	v_pk_mul_f32 v[102:103], v[102:103], v[146:147]
	v_pk_mul_f32 v[104:105], v[104:105], v[148:149]
	v_pk_mul_f32 v[98:99], v[98:99], v[150:151]
	v_pk_mul_f32 v[100:101], v[100:101], v[152:153]
	v_cvt_pk_bf16_f32 v162, v102, v103
	v_cvt_pk_bf16_f32 v163, v104, v105
	v_cvt_pk_bf16_f32 v164, v98, v99
	v_cvt_pk_bf16_f32 v165, v100, v101
	global_store_dwordx4 v190, v[162:165], s[10:11] sc1
	v_add_u32_e32 v190, s30, v190
	v_exp_f32_e32 v154, v154
	v_exp_f32_e32 v155, v155
	v_exp_f32_e32 v156, v156
	v_exp_f32_e32 v157, v157
	v_exp_f32_e32 v158, v158
	v_exp_f32_e32 v159, v159
	v_exp_f32_e32 v160, v160
	v_exp_f32_e32 v161, v161
	v_pk_mul_f32 v[82:83], v[82:83], v[70:71]
	v_pk_mul_f32 v[84:85], v[84:85], v[72:73]
	v_pk_mul_f32 v[78:79], v[78:79], v[66:67]
	v_pk_mul_f32 v[80:81], v[80:81], v[68:69]
; __device__ __forceinline__ unsigned cvt_pk_bf16(float lo, float hi) { unsigned r; asm volatile("v_cvt_pk_bf16_f32 %0, %1, %2" : "=v"(r) : "v"(lo), "v"(hi)); return r; }
; __device__ __forceinline__ float silu_f(float g) { return g * __builtin_amdgcn_rcpf(1.0f + __builtin_amdgcn_exp2f(g * -1.4426950408889634f)); }
;     __device__ __forceinline__ void operator()(const f32x4 (&acc)[2][2][4][2], const Unit& u, int wr, int wc, int fr, int fq) const {
;     ...
;             for (int m = 0; m < 4; ++m) { const int row = row0 + ai * HALF + m * 16; const float rs = rsv[ai][m];
;                 f32x4 g0 = acc[ai][0][m][0] * rs, g1 = acc[ai][0][m][1] * rs; const f32x4 t0 = acc[ai][1][m][0] * rs, t1 = acc[ai][1][m][1] * rs;
;                 if (silu) {
; #pragma unroll
;                     for (int j = 0; j < 4; ++j) { g0[j] = silu_f(g0[j]); g1[j] = silu_f(g1[j]); } }
;                 g0 = g0 * t0; g1 = g1 * t1;
;                 u32x4 w; w.x = cvt_pk_bf16(g0[0], g0[1]); w.y = cvt_pk_bf16(g0[2], g0[3]); w.z = cvt_pk_bf16(g1[0], g1[1]); w.w = cvt_pk_bf16(g1[2], g1[3]);
;                 *(u32x4*)(O + (size_t)row * ldc + col0 + (size_t)(row >> 12) * adj) = w; }
	v_pk_fma_f32 v[154:155], v[154:155], v[246:247], v[246:247] op_sel:[0,1,1] op_sel_hi:[1,1,1]
	v_pk_fma_f32 v[156:157], v[156:157], v[246:247], v[246:247] op_sel:[0,1,1] op_sel_hi:[1,1,1]
	v_pk_fma_f32 v[158:159], v[158:159], v[246:247], v[246:247] op_sel:[0,1,1] op_sel_hi:[1,1,1]
	v_pk_fma_f32 v[160:161], v[160:161], v[246:247], v[246:247] op_sel:[0,1,1] op_sel_hi:[1,1,1]
	v_rcp_f32_e32 v154, v154
	v_rcp_f32_e32 v155, v155
	v_rcp_f32_e32 v156, v156
	v_rcp_f32_e32 v157, v157
	v_rcp_f32_e32 v158, v158
	v_rcp_f32_e32 v159, v159
	v_rcp_f32_e32 v160, v160
	v_rcp_f32_e32 v161, v161
	v_pk_mul_f32 v[146:147], v[62:63], v[248:249] op_sel_hi:[1,0]
	v_pk_mul_f32 v[148:149], v[64:65], v[248:249] op_sel_hi:[1,0]
	v_pk_mul_f32 v[150:151], v[58:59], v[248:249] op_sel_hi:[1,0]
	v_pk_mul_f32 v[152:153], v[60:61], v[248:249] op_sel_hi:[1,0]
	v_pk_mul_f32 v[82:83], v[82:83], v[154:155]
	v_pk_mul_f32 v[84:85], v[84:85], v[156:157]
	v_pk_mul_f32 v[78:79], v[78:79], v[158:159]
	v_pk_mul_f32 v[80:81], v[80:81], v[160:161]
	v_cvt_pk_bf16_f32 v166, v82, v83
	v_cvt_pk_bf16_f32 v167, v84, v85
	v_cvt_pk_bf16_f32 v168, v78, v79
	v_cvt_pk_bf16_f32 v169, v80, v81
	global_store_dwordx4 v190, v[166:169], s[10:11] sc1
	v_add_u32_e32 v190, s31, v190
	v_exp_f32_e32 v146, v146
	v_exp_f32_e32 v147, v147
	v_exp_f32_e32 v148, v148
	v_exp_f32_e32 v149, v149
	v_exp_f32_e32 v150, v150
	v_exp_f32_e32 v151, v151
	v_exp_f32_e32 v152, v152
	v_exp_f32_e32 v153, v153
	v_pk_mul_f32 v[62:63], v[62:63], v[54:55]
	v_pk_mul_f32 v[64:65], v[64:65], v[56:57]
	v_pk_mul_f32 v[58:59], v[58:59], v[50:51]
	v_pk_mul_f32 v[60:61], v[60:61], v[52:53]
	v_pk_fma_f32 v[146:147], v[146:147], v[248:249], v[248:249] op_sel:[0,1,1] op_sel_hi:[1,1,1]
	v_pk_fma_f32 v[148:149], v[148:149], v[248:249], v[248:249] op_sel:[0,1,1] op_sel_hi:[1,1,1]
	v_pk_fma_f32 v[150:151], v[150:151], v[248:249], v[248:249] op_sel:[0,1,1] op_sel_hi:[1,1,1]
	v_pk_fma_f32 v[152:153], v[152:153], v[248:249], v[248:249] op_sel:[0,1,1] op_sel_hi:[1,1,1]
	v_rcp_f32_e32 v146, v146
	v_rcp_f32_e32 v147, v147
	v_rcp_f32_e32 v148, v148
	v_rcp_f32_e32 v149, v149
	v_rcp_f32_e32 v150, v150
	v_rcp_f32_e32 v151, v151
	v_rcp_f32_e32 v152, v152
	v_rcp_f32_e32 v153, v153
	v_pk_mul_f32 v[154:155], v[46:47], v[250:251] op_sel_hi:[1,0]
	v_pk_mul_f32 v[156:157], v[48:49], v[250:251] op_sel_hi:[1,0]
	v_pk_mul_f32 v[158:159], v[42:43], v[250:251] op_sel_hi:[1,0]
	v_pk_mul_f32 v[160:161], v[44:45], v[250:251] op_sel_hi:[1,0]
	v_pk_mul_f32 v[62:63], v[62:63], v[146:147]
	v_pk_mul_f32 v[64:65], v[64:65], v[148:149]
	v_pk_mul_f32 v[58:59], v[58:59], v[150:151]
	v_pk_mul_f32 v[60:61], v[60:61], v[152:153]
	v_cvt_pk_bf16_f32 v162, v62, v63
	v_cvt_pk_bf16_f32 v163, v64, v65
	v_cvt_pk_bf16_f32 v164, v58, v59
	v_cvt_pk_bf16_f32 v165, v60, v61
	global_store_dwordx4 v190, v[162:165], s[10:11] sc1
	v_add_u32_e32 v190, s30, v190
	v_exp_f32_e32 v154, v154
	v_exp_f32_e32 v155, v155
	v_exp_f32_e32 v156, v156
	v_exp_f32_e32 v157, v157
	v_exp_f32_e32 v158, v158
	v_exp_f32_e32 v159, v159
	v_exp_f32_e32 v160, v160
	v_exp_f32_e32 v161, v161
	v_pk_mul_f32 v[46:47], v[46:47], v[38:39]
	v_pk_mul_f32 v[48:49], v[48:49], v[40:41]
	v_pk_mul_f32 v[42:43], v[42:43], v[34:35]
	v_pk_mul_f32 v[44:45], v[44:45], v[36:37]
	v_pk_fma_f32 v[154:155], v[154:155], v[250:251], v[250:251] op_sel:[0,1,1] op_sel_hi:[1,1,1]
	v_pk_fma_f32 v[156:157], v[156:157], v[250:251], v[250:251] op_sel:[0,1,1] op_sel_hi:[1,1,1]
	v_pk_fma_f32 v[158:159], v[158:159], v[250:251], v[250:251] op_sel:[0,1,1] op_sel_hi:[1,1,1]
	v_pk_fma_f32 v[160:161], v[160:161], v[250:251], v[250:251] op_sel:[0,1,1] op_sel_hi:[1,1,1]
	v_rcp_f32_e32 v154, v154
	v_rcp_f32_e32 v155, v155
	v_rcp_f32_e32 v156, v156
	v_rcp_f32_e32 v157, v157
	v_rcp_f32_e32 v158, v158
	v_rcp_f32_e32 v159, v159
	v_rcp_f32_e32 v160, v160
	v_rcp_f32_e32 v161, v161
; __device__ __forceinline__ unsigned cvt_pk_bf16(float lo, float hi) { unsigned r; asm volatile("v_cvt_pk_bf16_f32 %0, %1, %2" : "=v"(r) : "v"(lo), "v"(hi)); return r; }
; __device__ __forceinline__ float silu_f(float g) { return g * __builtin_amdgcn_rcpf(1.0f + __builtin_amdgcn_exp2f(g * -1.4426950408889634f)); }
; #define PG8_BAR __builtin_amdgcn_s_barrier()
;     __device__ __forceinline__ void operator()(const f32x4 (&acc)[2][2][4][2], const Unit& u, int wr, int wc, int fr, int fq) const {
;     ...
;             for (int m = 0; m < 4; ++m) { const int row = row0 + ai * HALF + m * 16; const float rs = rsv[ai][m];
;                 f32x4 g0 = acc[ai][0][m][0] * rs, g1 = acc[ai][0][m][1] * rs; const f32x4 t0 = acc[ai][1][m][0] * rs, t1 = acc[ai][1][m][1] * rs;
;                 if (silu) {
; #pragma unroll
;                     for (int j = 0; j < 4; ++j) { g0[j] = silu_f(g0[j]); g1[j] = silu_f(g1[j]); } }
;                 g0 = g0 * t0; g1 = g1 * t1;
;                 u32x4 w; w.x = cvt_pk_bf16(g0[0], g0[1]); w.y = cvt_pk_bf16(g0[2], g0[3]); w.z = cvt_pk_bf16(g1[0], g1[1]); w.w = cvt_pk_bf16(g1[2], g1[3]);
;                 *(u32x4*)(O + (size_t)row * ldc + col0 + (size_t)(row >> 12) * adj) = w; }
; template <class Epi, bool ALIGN_EPI>
; __device__ __forceinline__ void gemm_phase(LAS unsigned char* lds, const Gemm g, const StaticOrder& S, const Epi& E) {
;     ...
;         if constexpr (ALIGN_EPI) { if (wr == 0) PG8_BAR; }
	v_pk_mul_f32 v[146:147], v[30:31], v[252:253] op_sel_hi:[1,0]
	v_pk_mul_f32 v[148:149], v[32:33], v[252:253] op_sel_hi:[1,0]
	v_pk_mul_f32 v[150:151], v[26:27], v[252:253] op_sel_hi:[1,0]
	v_pk_mul_f32 v[152:153], v[28:29], v[252:253] op_sel_hi:[1,0]
	v_pk_mul_f32 v[46:47], v[46:47], v[154:155]
	v_pk_mul_f32 v[48:49], v[48:49], v[156:157]
	v_pk_mul_f32 v[42:43], v[42:43], v[158:159]
	v_pk_mul_f32 v[44:45], v[44:45], v[160:161]
	v_cvt_pk_bf16_f32 v166, v46, v47
	v_cvt_pk_bf16_f32 v167, v48, v49
	v_cvt_pk_bf16_f32 v168, v42, v43
	v_cvt_pk_bf16_f32 v169, v44, v45
	global_store_dwordx4 v190, v[166:169], s[10:11] sc1
	v_add_u32_e32 v190, s30, v190
	v_exp_f32_e32 v146, v146
	v_exp_f32_e32 v147, v147
	v_exp_f32_e32 v148, v148
	v_exp_f32_e32 v149, v149
	v_exp_f32_e32 v150, v150
	v_exp_f32_e32 v151, v151
	v_exp_f32_e32 v152, v152
	v_exp_f32_e32 v153, v153
	v_pk_mul_f32 v[30:31], v[30:31], v[22:23]
	v_pk_mul_f32 v[32:33], v[32:33], v[24:25]
	v_pk_mul_f32 v[26:27], v[26:27], v[18:19]
	v_pk_mul_f32 v[28:29], v[28:29], v[20:21]
	v_pk_fma_f32 v[146:147], v[146:147], v[252:253], v[252:253] op_sel:[0,1,1] op_sel_hi:[1,1,1]
	v_pk_fma_f32 v[148:149], v[148:149], v[252:253], v[252:253] op_sel:[0,1,1] op_sel_hi:[1,1,1]
	v_pk_fma_f32 v[150:151], v[150:151], v[252:253], v[252:253] op_sel:[0,1,1] op_sel_hi:[1,1,1]
	v_pk_fma_f32 v[152:153], v[152:153], v[252:253], v[252:253] op_sel:[0,1,1] op_sel_hi:[1,1,1]
	v_rcp_f32_e32 v146, v146
	v_rcp_f32_e32 v147, v147
	v_rcp_f32_e32 v148, v148
	v_rcp_f32_e32 v149, v149
	v_rcp_f32_e32 v150, v150
	v_rcp_f32_e32 v151, v151
	v_rcp_f32_e32 v152, v152
	v_rcp_f32_e32 v153, v153
	v_pk_mul_f32 v[154:155], v[14:15], v[214:215] op_sel_hi:[1,0]
	v_pk_mul_f32 v[156:157], v[16:17], v[214:215] op_sel_hi:[1,0]
	v_pk_mul_f32 v[158:159], v[10:11], v[214:215] op_sel_hi:[1,0]
	v_pk_mul_f32 v[160:161], v[12:13], v[214:215] op_sel_hi:[1,0]
	v_pk_mul_f32 v[30:31], v[30:31], v[146:147]
	v_pk_mul_f32 v[32:33], v[32:33], v[148:149]
	v_pk_mul_f32 v[26:27], v[26:27], v[150:151]
	v_pk_mul_f32 v[28:29], v[28:29], v[152:153]
	v_cvt_pk_bf16_f32 v162, v30, v31
	v_cvt_pk_bf16_f32 v163, v32, v33
	v_cvt_pk_bf16_f32 v164, v26, v27
	v_cvt_pk_bf16_f32 v165, v28, v29
	global_store_dwordx4 v190, v[162:165], s[10:11] sc1
	v_add_u32_e32 v190, s30, v190
	v_exp_f32_e32 v154, v154
	v_exp_f32_e32 v155, v155
	v_exp_f32_e32 v156, v156
	v_exp_f32_e32 v157, v157
	v_exp_f32_e32 v158, v158
	v_exp_f32_e32 v159, v159
	v_exp_f32_e32 v160, v160
	v_exp_f32_e32 v161, v161
	v_pk_mul_f32 v[14:15], v[14:15], v[6:7]
	v_pk_mul_f32 v[16:17], v[16:17], v[8:9]
	v_pk_mul_f32 v[10:11], v[10:11], v[2:3]
	v_pk_mul_f32 v[12:13], v[12:13], v[4:5]
	v_pk_fma_f32 v[154:155], v[154:155], v[214:215], v[214:215] op_sel:[0,1,1] op_sel_hi:[1,1,1]
	v_pk_fma_f32 v[156:157], v[156:157], v[214:215], v[214:215] op_sel:[0,1,1] op_sel_hi:[1,1,1]
	v_pk_fma_f32 v[158:159], v[158:159], v[214:215], v[214:215] op_sel:[0,1,1] op_sel_hi:[1,1,1]
	v_pk_fma_f32 v[160:161], v[160:161], v[214:215], v[214:215] op_sel:[0,1,1] op_sel_hi:[1,1,1]
	v_rcp_f32_e32 v154, v154
	v_rcp_f32_e32 v155, v155
	v_rcp_f32_e32 v156, v156
	v_rcp_f32_e32 v157, v157
	v_rcp_f32_e32 v158, v158
	v_rcp_f32_e32 v159, v159
	v_rcp_f32_e32 v160, v160
	v_rcp_f32_e32 v161, v161
	v_pk_mul_f32 v[14:15], v[14:15], v[154:155]
	v_pk_mul_f32 v[16:17], v[16:17], v[156:157]
	v_pk_mul_f32 v[10:11], v[10:11], v[158:159]
	v_pk_mul_f32 v[12:13], v[12:13], v[160:161]
	v_cvt_pk_bf16_f32 v166, v14, v15
	v_cvt_pk_bf16_f32 v167, v16, v17
	v_cvt_pk_bf16_f32 v168, v10, v11
	v_cvt_pk_bf16_f32 v169, v12, v13
	global_store_dwordx4 v190, v[166:169], s[10:11] sc1
	v_readlane_b32 s4, v254, 46
	v_readlane_b32 s5, v254, 47
	s_cmp_lg_u64 s[4:5], 0
	s_cbranch_scc0 .Lep_fast_nobar
	s_barrier
.Lep_fast_nobar:
	s_andn2_b64 vcc, exec, s[8:9]
	s_mov_b64 s[4:5], -1
	s_branch .Lep_join
